# GEMM phase prologue: both K-tile stage groups issued before the first wait (one HBM round trip less per phase)
# baseline (speedup 1.0000x reference)
; #define PG8_STAGE(bufoff, gbase, voff) do { _Pragma("unroll") for (int _i = 0; _i < 2; ++_i) \
;         __builtin_amdgcn_global_load_lds((const unsigned*)((const char*)(gbase) + (voff)[_i]), (PG8_LAS unsigned*)(lds + (bufoff) + ldsw + _i * 8192), 16, 0, 0); } while (0)
; #define PG8_WAIT_V(n) asm volatile("s_waitcnt vmcnt(" #n ")" ::: "memory")
; #define PG8_BAR __builtin_amdgcn_s_barrier()
; template <class Epi, class Sched, bool ALIGN_EPI = false, bool SP2 = false>
; __device__ __forceinline__ void gemm_phase(PG8_LAS unsigned char* lds, const Gemm g, const Sched& S, const Epi& E) {
;     ...
;         PG8_STAGE(PG8_SB(0, 0), cB, voffB); PG8_STAGE(PG8_SB(0, 1), cB + hstep, voffB); PG8_STAGE(PG8_SA(0, 0), cA, voffA); PG8_STAGE(PG8_SA(0, 1), cA + hstep, voffA);
;         if (wr == 1) PG8_BAR;
;         PG8_WAIT_V(2); PG8_BAR;
;         PG8_STAGE(PG8_SB(1, 0), cB + kstep, voffB); PG8_STAGE(PG8_SA(1, 0), cA + kstep, voffA); PG8_STAGE(PG8_SB(1, 1), cB + hstep + kstep, voffB);
;         PG8_WAIT_V(6); PG8_BAR;
; __global__ void __launch_bounds__(NTHR, 2) hymba_fwd(Args a) {
;     ...
;             pg8::Gemm g{XB, (const bf16_t*)(wl + W_IN), M, PL, D}; pg8::StaticOrder S; S.init(M, PL, G, (int)blockIdx.x);
;             pg8::EpiProj E{RB, ssq + (size_t)(3 * l + 1) * M * 16, PL, lds + RSC_OFF + tid * 32, -1};
;             pg8::gemm_phase<pg8::EpiProj, pg8::StaticOrder, true, true>(lds, g, S, E);
.LBB0_567:
	s_mul_i32 s38, s80, 0x300000
	s_lshl_b64 s[8:9], s[38:39], 2
	v_readlane_b32 s7, v253, 7
	s_add_u32 s7, s7, s8
	v_readlane_b32 s8, v253, 8
	s_addc_u32 s8, s8, s9
	v_lshrrev_b32_e32 v18, 1, v12
	s_add_u32 s12, s7, 0x400000
	v_and_b32_e32 v18, 24, v18
	v_readlane_b32 s20, v254, 7
	s_addc_u32 s13, s8, 0
	v_and_b32_e32 v13, 15, v12
	v_lshlrev_b32_e32 v19, 1, v18
	v_lshlrev_b32_e32 v12, 2, v12
	s_lshl_b32 s1, s1, 5
	v_mov_b32_e32 v173, v8
	v_readlane_b32 s21, v254, 8
	v_lshl_or_b32 v9, s6, 6, v13
	v_lshl_or_b32 v13, v13, 6, v19
	s_lshl_b32 s6, s6, 13
	v_and_b32_e32 v12, 32, v12
	s_and_b32 s1, s1, 0x60
	s_add_i32 m0, s55, 0x18000
	v_lshl_add_u64 v[0:1], v[0:1], 0, s[44:45]
	v_lshl_add_u64 v[14:15], s[20:21], 0, v[172:173]
	v_mov_b32_e32 v157, v8
	v_bitop3_b32 v19, v13, s6, v12 bitop3:0xde
	s_lshl_b32 s6, s1, 7
	global_load_lds_dwordx4 v[0:1], off
	v_lshl_add_u64 v[0:1], v[2:3], 0, s[44:45]
	s_add_i32 m0, s55, 0x1a000
	s_add_i32 s38, s55, 0x8000
	s_add_i32 s69, s55, 0xa000
	v_lshl_add_u64 v[16:17], s[20:21], 0, v[156:157]
	v_bitop3_b32 v163, v13, s6, v12 bitop3:0xde
	global_load_lds_dwordx4 v[0:1], off
	v_lshl_add_u64 v[0:1], v[14:15], 0, s[44:45]
	s_mov_b32 m0, s38
	s_add_u32 s6, s24, 0x40080
	global_load_lds_dwordx4 v[0:1], off
	v_lshl_add_u64 v[0:1], v[16:17], 0, s[44:45]
	s_mov_b32 m0, s69
	s_addc_u32 s7, s25, 0
	global_load_lds_dwordx4 v[0:1], off
	s_add_i32 m0, s55, 0x1c000
	v_lshl_add_u64 v[0:1], s[6:7], 0, v[170:171]
	global_load_lds_dwordx4 v[0:1], off
	v_lshl_add_u64 v[0:1], s[6:7], 0, v[154:155]
	s_add_i32 m0, s55, 0x1e000
	s_cmpk_lt_u32 s0, 0x100
	global_load_lds_dwordx4 v[0:1], off
	s_waitcnt vmcnt(6)
	s_barrier
	v_lshlrev_b32_e32 v0, 14, v10
	v_and_b32_e32 v0, 0xffff8000, v0
	v_lshl_add_u32 v0, v7, 11, v0
	v_and_b32_e32 v1, 1, v10
	v_lshl_or_b32 v0, v1, 6, v0
	v_lshl_add_u32 v174, v11, 1, v0
	v_lshlrev_b32_e32 v0, 14, v4
	v_and_b32_e32 v0, 0xffff8000, v0
	s_waitcnt vmcnt(6)
	v_lshl_add_u32 v0, v5, 11, v0
	v_and_b32_e32 v1, 1, v4
	v_lshl_or_b32 v0, v1, 6, v0
	v_readlane_b32 s4, v254, 5
	s_cselect_b64 s[14:15], -1, 0
	v_or_b32_e32 v194, s1, v18
	v_mov_b32_e32 v175, v8
	v_lshl_add_u32 v176, v6, 1, v0
	v_mov_b32_e32 v177, v8
	s_mov_b32 s70, 0
	s_mov_b32 s1, -1
	v_add_u32_e32 v195, 0, v19
	v_readlane_b32 s0, v254, 13
	s_mov_b32 s71, s4
	s_mov_b64 s[8:9], s[20:21]
	s_barrier
	v_readlane_b32 s5, v254, 6
	s_branch .LBB0_570

; #define PG8_STAGE(bufoff, gbase, voff) do { _Pragma("unroll") for (int _i = 0; _i < 2; ++_i) \
;         __builtin_amdgcn_global_load_lds((const unsigned*)((const char*)(gbase) + (voff)[_i]), (PG8_LAS unsigned*)(lds + (bufoff) + ldsw + _i * 8192), 16, 0, 0); } while (0)
; #define PG8_WAIT_V(n) asm volatile("s_waitcnt vmcnt(" #n ")" ::: "memory")
; #define PG8_BAR __builtin_amdgcn_s_barrier()
; template <class Epi, class Sched, bool ALIGN_EPI = false, bool SP2 = false>
; __device__ __forceinline__ void gemm_phase(PG8_LAS unsigned char* lds, const Gemm g, const Sched& S, const Epi& E) {
;     ...
;         PG8_STAGE(PG8_SB(0, 0), cB, voffB); PG8_STAGE(PG8_SB(0, 1), cB + hstep, voffB); PG8_STAGE(PG8_SA(0, 0), cA, voffA); PG8_STAGE(PG8_SA(0, 1), cA + hstep, voffA);
;         if (wr == 1) PG8_BAR;
;         PG8_WAIT_V(2); PG8_BAR;
;         PG8_STAGE(PG8_SB(1, 0), cB + kstep, voffB); PG8_STAGE(PG8_SA(1, 0), cA + kstep, voffA); PG8_STAGE(PG8_SB(1, 1), cB + hstep + kstep, voffB);
;         PG8_WAIT_V(6); PG8_BAR;
; __global__ void __launch_bounds__(NTHR, 2) hymba_fwd(Args a) {
;     ...
;             const int KK = (k == 5) ? D : FF;
;             pg8::Gemm g{k == 5 ? YB : RB, (const bf16_t*)(wl + (k == 1 ? W_D1 : (k == 5 ? W_OUT : W_D2))), M, D, KK}; pg8::RevOrder S; S.init(M, D, G, (int)blockIdx.x);
;             pg8::EpiRes E{XB, ssq + (size_t)(3 * l + (k == 1 ? 1 : (k == 5 ? 2 : 3))) * M * 16, k == 5 ? 1.0f : 0.5f};
;             pg8::gemm_phase<pg8::EpiRes, pg8::RevOrder, true, true>(lds, g, S, E);
.LBB0_637:
	s_and_b64 s[16:17], s[8:9], exec
	s_cselect_b32 s16, 2, 3
	s_and_b64 s[10:11], s[10:11], exec
	s_mul_i32 s20, s80, 3
	s_cselect_b32 s10, 1, s16
	s_add_i32 s10, s10, s20
	s_lshl_b32 s38, s10, 20
	s_lshl_b64 s[10:11], s[38:39], 2
	v_readlane_b32 s16, v253, 7
	s_add_u32 s16, s16, s10
	v_readlane_b32 s10, v253, 8
	s_addc_u32 s17, s10, s11
	s_add_i32 m0, s68, 0x18000
	v_lshl_add_u64 v[0:1], v[0:1], 0, s[44:45]
	global_load_lds_dwordx4 v[0:1], off
	v_lshl_add_u64 v[0:1], v[2:3], 0, s[44:45]
	s_add_i32 m0, s68, 0x1a000
	s_add_i32 s72, s68, 0x8000
	global_load_lds_dwordx4 v[0:1], off
	v_lshl_add_u64 v[0:1], v[10:11], 0, s[44:45]
	s_mov_b32 m0, s72
	s_add_i32 s73, s68, 0xa000
	global_load_lds_dwordx4 v[0:1], off
	v_lshl_add_u64 v[0:1], v[12:13], 0, s[44:45]
	s_mov_b32 m0, s73
	s_and_b32 s81, s1, 3
	global_load_lds_dwordx4 v[0:1], off
	s_add_i32 m0, s68, 0x1c000
	v_lshl_add_u64 v[0:1], v[4:5], 0, s[44:45]
	global_load_lds_dwordx4 v[0:1], off
	v_lshl_add_u64 v[0:1], v[6:7], 0, s[44:45]
	s_add_i32 m0, s68, 0x1e000
	s_lshl_b32 s1, s19, 13
	global_load_lds_dwordx4 v[0:1], off
	s_waitcnt vmcnt(6)
	s_barrier
	v_bfe_u32 v0, v14, 4, 2
	v_and_b32_e32 v1, 15, v14
	v_lshlrev_b32_e32 v3, 4, v0
	v_lshl_or_b32 v9, s19, 6, v1
	v_lshl_or_b32 v1, v1, 6, v3
	v_lshlrev_b32_e32 v3, 2, v14
	v_and_b32_e32 v3, 32, v3
	v_cndmask_b32_e64 v138, 0.5, 1.0, s[8:9]
	v_lshlrev_b32_e32 v2, 3, v0
	v_bitop3_b32 v4, v1, s1, v3 bitop3:0xde
	s_lshl_b32 s1, s81, 12
	v_cmp_eq_u32_e64 s[8:9], 0, v0
	v_add_u32_e32 v0, v17, v15
	s_lshr_b32 s0, s0, 6
	v_bitop3_b32 v150, v1, s1, v3 bitop3:0xde
	v_add_lshl_u32 v0, v0, v16, 1
	v_mov_b32_e32 v1, v8
	s_waitcnt vmcnt(6)
	s_add_i32 s1, s0, -2
	v_lshl_add_u64 v[142:143], s[12:13], 0, v[0:1]
	v_add_u32_e32 v0, v20, v18
	s_cmpk_lt_u32 s18, 0x100
	v_add_lshl_u32 v0, v0, v19, 1
	v_lshl_or_b32 v151, s81, 5, v2
	s_cselect_b64 s[18:19], -1, 0
	s_mov_b32 s38, 0
	v_mov_b32_e32 v140, v138
	v_mov_b32_e32 v141, v138
	v_lshl_add_u64 v[144:145], s[12:13], 0, v[0:1]
	v_add_u32_e32 v152, 0, v4
	s_barrier
	s_branch .LBB0_640

; #define PG8_STAGE(bufoff, gbase, voff) do { _Pragma("unroll") for (int _i = 0; _i < 2; ++_i) \
;         __builtin_amdgcn_global_load_lds((const unsigned*)((const char*)(gbase) + (voff)[_i]), (PG8_LAS unsigned*)(lds + (bufoff) + ldsw + _i * 8192), 16, 0, 0); } while (0)
; #define PG8_WAIT_V(n) asm volatile("s_waitcnt vmcnt(" #n ")" ::: "memory")
; #define PG8_BAR __builtin_amdgcn_s_barrier()
; template <class Epi, class Sched, bool ALIGN_EPI = false, bool SP2 = false>
; __device__ __forceinline__ void gemm_phase(PG8_LAS unsigned char* lds, const Gemm g, const Sched& S, const Epi& E) {
;     ...
;         PG8_STAGE(PG8_SB(0, 0), cB, voffB); PG8_STAGE(PG8_SB(0, 1), cB + hstep, voffB); PG8_STAGE(PG8_SA(0, 0), cA, voffA); PG8_STAGE(PG8_SA(0, 1), cA + hstep, voffA);
;         if (wr == 1) PG8_BAR;
;         PG8_WAIT_V(2); PG8_BAR;
;         PG8_STAGE(PG8_SB(1, 0), cB + kstep, voffB); PG8_STAGE(PG8_SA(1, 0), cA + kstep, voffA); PG8_STAGE(PG8_SB(1, 1), cB + hstep + kstep, voffB);
;         PG8_WAIT_V(6); PG8_BAR;
; __global__ void __launch_bounds__(NTHR, 2) hymba_fwd(Args a) {
;     ...
;             pg8::Gemm g{XB, (const bf16_t*)(wl + (k == 0 ? W_GU1 : W_GU2)), M, NGU, D}; pg8::StaticOrder S; S.init(M, NGU, G, (int)blockIdx.x);
;             pg8::EpiGU E{RB, ssq + (size_t)(3 * l + (k == 0 ? 0 : 2)) * M * 16, FF, lds + RSC_OFF + tid * 32, -1};
;             pg8::gemm_phase<pg8::EpiGU, pg8::StaticOrder, true, true>(lds, g, S, E);
.LBB0_692:
	s_and_b64 s[6:7], s[6:7], exec
	s_mul_i32 s80, s80, 3
	s_cselect_b32 s6, 0, 2
	s_add_i32 s6, s6, s80
	s_lshl_b32 s38, s6, 20
	s_lshl_b64 s[6:7], s[38:39], 2
	v_readlane_b32 s10, v253, 7
	s_add_u32 s10, s10, s6
	v_readlane_b32 s6, v253, 8
	v_readlane_b32 s22, v253, 63
	s_addc_u32 s11, s6, s7
	s_lshl_b32 s6, s14, 5
	v_mov_b32_e32 v173, v8
	v_readlane_b32 s23, v254, 0
	s_and_b32 s14, s6, 0x60
	s_add_i32 m0, s53, 0x18000
	v_lshl_add_u64 v[0:1], v[0:1], 0, s[44:45]
	v_lshl_add_u64 v[14:15], s[22:23], 0, v[172:173]
	v_mov_b32_e32 v157, v8
	s_lshl_b32 s15, s13, 13
	s_lshl_b32 s16, s14, 7
	global_load_lds_dwordx4 v[0:1], off
	v_lshl_add_u64 v[0:1], v[2:3], 0, s[44:45]
	s_add_i32 m0, s53, 0x1a000
	s_add_i32 s38, s53, 0x8000
	s_add_i32 s66, s53, 0xa000
	v_lshl_add_u64 v[16:17], s[22:23], 0, v[156:157]
	global_load_lds_dwordx4 v[0:1], off
	v_lshl_add_u64 v[0:1], v[14:15], 0, s[44:45]
	s_mov_b32 m0, s38
	s_add_u32 s6, s24, 0x40080
	global_load_lds_dwordx4 v[0:1], off
	v_lshl_add_u64 v[0:1], v[16:17], 0, s[44:45]
	s_mov_b32 m0, s66
	s_addc_u32 s7, s25, 0
	global_load_lds_dwordx4 v[0:1], off
	s_add_i32 m0, s53, 0x1c000
	v_lshl_add_u64 v[0:1], s[6:7], 0, v[170:171]
	global_load_lds_dwordx4 v[0:1], off
	v_lshl_add_u64 v[0:1], s[6:7], 0, v[154:155]
	s_add_i32 m0, s53, 0x1e000
	s_cmpk_lt_u32 s12, 0x100
	global_load_lds_dwordx4 v[0:1], off
	s_waitcnt vmcnt(6)
	s_barrier
	v_lshrrev_b32_e32 v1, 1, v4
	v_and_b32_e32 v1, 24, v1
	v_and_b32_e32 v0, 15, v4
	v_lshlrev_b32_e32 v2, 1, v1
	v_lshl_or_b32 v9, s13, 6, v0
	v_lshl_or_b32 v0, v0, 6, v2
	v_lshlrev_b32_e32 v2, 2, v4
	v_and_b32_e32 v2, 32, v2
	v_bitop3_b32 v3, v0, s15, v2 bitop3:0xde
	v_bitop3_b32 v163, v0, s16, v2 bitop3:0xde
	v_lshlrev_b32_e32 v0, 14, v11
	v_and_b32_e32 v0, 0xffff8000, v0
	v_or_b32_e32 v188, s14, v1
	v_lshl_add_u32 v0, v10, 11, v0
	v_and_b32_e32 v1, 1, v11
	v_lshl_or_b32 v0, v1, 6, v0
	v_lshl_add_u32 v174, v12, 1, v0
	v_lshlrev_b32_e32 v0, 14, v5
	v_and_b32_e32 v0, 0xffff8000, v0
	s_waitcnt vmcnt(6)
	v_lshl_add_u32 v0, v6, 11, v0
	v_and_b32_e32 v1, 1, v5
	v_lshl_or_b32 v0, v1, 6, v0
	v_readlane_b32 s4, v253, 61
	s_mov_b32 s67, 0
	s_cselect_b64 s[12:13], -1, 0
	v_mov_b32_e32 v175, v8
	v_lshl_add_u32 v176, v7, 1, v0
	v_mov_b32_e32 v177, v8
	s_mov_b32 s70, -1
	v_add_u32_e32 v189, 0, v3
	v_readlane_b32 s69, v254, 14
	s_mov_b32 s68, s4
	s_movk_i32 s4, 0x2c1
	s_barrier
	v_readlane_b32 s5, v253, 62
	s_branch .LBB0_695
